# v112 + P0 / deferred weight-conversion outputs (XN rows, transposed bf16 weights) stored write-through (sc1)
# baseline (speedup 1.0000x reference)
.LBB0_10:
	s_lshl_b32 s4, s46, 6
	s_ashr_i32 s5, s4, 31
	s_lshl_b64 s[4:5], s[4:5], 2
	s_waitcnt lgkmcnt(0)
	s_add_u32 s4, s58, s4
	s_addc_u32 s5, s59, s5
	v_mul_lo_u32 v3, s54, v13
	v_mul_lo_u32 v11, s54, v13
	v_or_b32_e32 v13, 8, v12
	v_lshl_add_u64 v[46:47], s[4:5], 0, v[8:9]
	v_mul_lo_u32 v2, s55, v12
	v_mad_u64_u32 v[0:1], s[4:5], s54, v12, 0
	v_mul_lo_u32 v45, s55, v13
	v_mad_u64_u32 v[48:49], s[4:5], s54, v13, 0
	v_or_b32_e32 v13, 12, v12
	v_add3_u32 v1, v1, v3, v2
	v_or_b32_e32 v2, 4, v12
	v_add3_u32 v49, v49, v11, v45
	v_mul_lo_u32 v45, s55, v13
	v_mad_u64_u32 v[50:51], s[4:5], s54, v13, 0
	v_or_b32_e32 v13, 16, v12
	v_mul_lo_u32 v4, s55, v2
	v_mad_u64_u32 v[2:3], s[4:5], s54, v2, 0
	v_add3_u32 v51, v51, v11, v45
	v_mul_lo_u32 v45, s55, v13
	v_mad_u64_u32 v[56:57], s[4:5], s54, v13, 0
	v_add3_u32 v3, v3, v11, v4
	v_add3_u32 v57, v57, v11, v45
	v_lshl_add_u64 v[0:1], v[0:1], 2, v[46:47]
	v_lshl_add_u64 v[2:3], v[2:3], 2, v[46:47]
	v_lshl_add_u64 v[48:49], v[48:49], 2, v[46:47]
	v_lshl_add_u64 v[52:53], v[50:51], 2, v[46:47]
	v_lshl_add_u64 v[56:57], v[56:57], 2, v[46:47]
	global_load_dwordx4 v[4:7], v[0:1], off nt
	s_nop 0
	global_load_dwordx4 v[0:3], v[2:3], off nt
	s_nop 0
	global_load_dwordx4 v[48:51], v[48:49], off nt
	s_nop 0
	global_load_dwordx4 v[52:55], v[52:53], off nt
	v_or_b32_e32 v13, 20, v12
	global_load_dwordx4 v[56:59], v[56:57], off nt
	v_mul_lo_u32 v62, s55, v13
	v_mad_u64_u32 v[60:61], s[4:5], s54, v13, 0
	v_or_b32_e32 v45, 24, v12
	v_add3_u32 v61, v61, v11, v62
	v_mul_lo_u32 v13, s55, v45
	v_mad_u64_u32 v[64:65], s[4:5], s54, v45, 0
	v_lshl_add_u64 v[60:61], v[60:61], 2, v[46:47]
	v_add3_u32 v65, v65, v11, v13
	global_load_dwordx4 v[60:63], v[60:61], off nt
	v_lshl_add_u64 v[64:65], v[64:65], 2, v[46:47]
	v_or_b32_e32 v13, 28, v12
	v_or_b32_e32 v45, 32, v12
	global_load_dwordx4 v[64:67], v[64:65], off nt
	v_mul_lo_u32 v73, s55, v13
	v_mad_u64_u32 v[68:69], s[4:5], s54, v13, 0
	v_mul_lo_u32 v13, s55, v45
	v_mad_u64_u32 v[70:71], s[4:5], s54, v45, 0
	v_or_b32_e32 v72, 36, v12
	v_add3_u32 v69, v69, v11, v73
	v_add3_u32 v71, v71, v11, v13
	v_mul_lo_u32 v45, s55, v72
	v_mad_u64_u32 v[76:77], s[4:5], s54, v72, 0
	v_lshl_add_u64 v[68:69], v[68:69], 2, v[46:47]
	v_lshl_add_u64 v[72:73], v[70:71], 2, v[46:47]
	global_load_dwordx4 v[68:71], v[68:69], off nt
	s_nop 0
	global_load_dwordx4 v[72:75], v[72:73], off nt
	v_or_b32_e32 v78, 40, v12
	v_add3_u32 v77, v77, v11, v45
	v_mul_lo_u32 v79, s55, v78
	v_or_b32_e32 v13, 48, v12
	s_ashr_i32 s57, s56, 31
	s_waitcnt vmcnt(8)
	v_pk_mul_f32 v[82:83], v[20:21], v[6:7] op_sel_hi:[0,1]
	v_or_b32_e32 v6, 44, v12
	v_pk_mul_f32 v[80:81], v[20:21], v[4:5] op_sel_hi:[0,1]
	s_waitcnt vmcnt(7)
	v_pk_mul_f32 v[84:85], v[16:17], v[0:1] op_sel_hi:[0,1]
	s_waitcnt vmcnt(4)
	v_pk_mul_f32 v[96:97], v[44:45], v[56:57] op_sel_hi:[0,1]
	v_pk_mul_f32 v[98:99], v[44:45], v[58:59] op_sel_hi:[0,1]
	v_mad_u64_u32 v[4:5], s[4:5], s54, v78, 0
	v_lshl_add_u64 v[0:1], v[76:77], 2, v[46:47]
	v_mul_lo_u32 v7, s55, v6
	v_mad_u64_u32 v[44:45], s[4:5], s54, v6, 0
	v_pk_mul_f32 v[86:87], v[16:17], v[2:3] op_sel_hi:[0,1]
	v_pk_mul_f32 v[92:93], v[32:33], v[52:53] op_sel_hi:[0,1]
	v_add3_u32 v5, v5, v11, v79
	global_load_dwordx4 v[0:3], v[0:1], off nt
	v_add3_u32 v45, v45, v11, v7
	v_mul_lo_u32 v16, s55, v13
	v_mad_u64_u32 v[52:53], s[4:5], s54, v13, 0
	v_lshl_add_u64 v[4:5], v[4:5], 2, v[46:47]
	v_lshl_add_u64 v[44:45], v[44:45], 2, v[46:47]
	v_add3_u32 v53, v53, v11, v16
	v_pk_mul_f32 v[88:89], v[34:35], v[48:49] op_sel_hi:[0,1]
	v_pk_mul_f32 v[90:91], v[34:35], v[50:51] op_sel_hi:[0,1]
	global_load_dwordx4 v[4:7], v[4:5], off nt
	v_or_b32_e32 v13, 52, v12
	global_load_dwordx4 v[48:51], v[44:45], off nt
	v_lshl_add_u64 v[44:45], v[52:53], 2, v[46:47]
	v_pk_mul_f32 v[94:95], v[32:33], v[54:55] op_sel_hi:[0,1]
	v_mul_lo_u32 v16, s55, v13
	global_load_dwordx4 v[52:55], v[44:45], off nt
	v_mad_u64_u32 v[44:45], s[4:5], s54, v13, 0
	v_add3_u32 v45, v45, v11, v16
	v_or_b32_e32 v16, 60, v12
	v_or_b32_e32 v20, 56, v12
	v_lshl_add_u64 v[12:13], v[44:45], 2, v[46:47]
	global_load_dwordx4 v[56:59], v[12:13], off nt
	v_mul_lo_u32 v32, s55, v20
	v_mad_u64_u32 v[12:13], s[4:5], s54, v20, 0
	v_add3_u32 v13, v13, v11, v32
	v_lshl_add_u64 v[12:13], v[12:13], 2, v[46:47]
	global_load_dwordx4 v[76:79], v[12:13], off nt
	v_mul_lo_u32 v20, s55, v16
	v_mad_u64_u32 v[12:13], s[4:5], s54, v16, 0
	v_add3_u32 v13, v13, v11, v20
	v_lshl_add_u64 v[12:13], v[12:13], 2, v[46:47]
	global_load_dwordx4 v[44:47], v[12:13], off nt
	v_add_u32_e32 v11, 0x410, v43
	ds_write2_b32 v11, v84, v85 offset1:1
	v_add_u32_e32 v11, 0x418, v43
	ds_write2_b32 v11, v86, v87 offset1:1
	v_add_u32_e32 v11, 0x820, v43
	ds_write2_b32 v11, v88, v89 offset1:1
	v_add_u32_e32 v11, 0x828, v43
	ds_write2_b32 v11, v90, v91 offset1:1
	v_add_u32_e32 v11, 0xc30, v43
	ds_write2_b32 v11, v92, v93 offset1:1
	v_add_u32_e32 v11, 0xc38, v43
	ds_write2_b32 v11, v94, v95 offset1:1
	v_add_u32_e32 v11, 0x1040, v43
	ds_write2_b32 v11, v96, v97 offset1:1
	v_add_u32_e32 v11, 0x1048, v43
	s_waitcnt vmcnt(10)
	v_pk_mul_f32 v[12:13], v[22:23], v[60:61] op_sel_hi:[0,1]
	ds_write2_b32 v11, v98, v99 offset1:1
	v_add_u32_e32 v11, 0x1450, v43
	v_pk_mul_f32 v[60:61], v[22:23], v[62:63] op_sel_hi:[0,1]
	ds_write2_b32 v11, v12, v13 offset1:1
	v_add_u32_e32 v11, 0x1458, v43
	s_waitcnt vmcnt(9)
	v_pk_mul_f32 v[62:63], v[38:39], v[64:65] op_sel_hi:[0,1]
	ds_write2_b32 v11, v60, v61 offset1:1
	v_add_u32_e32 v11, 0x1860, v43
	v_pk_mul_f32 v[64:65], v[38:39], v[66:67] op_sel_hi:[0,1]
	ds_write2_b32 v11, v62, v63 offset1:1
	v_add_u32_e32 v11, 0x1868, v43
	ds_write2_b32 v11, v64, v65 offset1:1
	v_add_u32_e32 v11, 0x1c70, v43
	s_waitcnt vmcnt(8)
	v_pk_mul_f32 v[12:13], v[14:15], v[68:69] op_sel_hi:[0,1]
	ds_write2_b32 v11, v12, v13 offset1:1
	ds_write2_b32 v43, v80, v81 offset1:1
	ds_write2_b32 v43, v82, v83 offset0:2 offset1:3
	v_pk_mul_f32 v[12:13], v[14:15], v[70:71] op_sel_hi:[0,1]
	v_add_u32_e32 v11, 0x1c78, v43
	ds_write2_b32 v11, v12, v13 offset1:1
	s_waitcnt vmcnt(7)
	v_pk_mul_f32 v[12:13], v[26:27], v[72:73] op_sel_hi:[0,1]
	v_add_u32_e32 v11, 0x2080, v43
	ds_write2_b32 v11, v12, v13 offset1:1
	v_pk_mul_f32 v[12:13], v[26:27], v[74:75] op_sel_hi:[0,1]
	v_add_u32_e32 v11, 0x2088, v43
	ds_write2_b32 v11, v12, v13 offset1:1
	v_add_u32_e32 v11, 0x2490, v43
	s_lshl_b64 s[4:5], s[56:57], 1
	v_add_u32_e32 v14, 0x400, v19
	s_waitcnt vmcnt(6)
	v_pk_mul_f32 v[0:1], v[18:19], v[0:1] op_sel_hi:[0,1]
	ds_write2_b32 v11, v0, v1 offset1:1
	v_pk_mul_f32 v[0:1], v[18:19], v[2:3] op_sel_hi:[0,1]
	v_add_u32_e32 v2, 0x2498, v43
	ds_write2_b32 v2, v0, v1 offset1:1
	v_add_u32_e32 v2, 0x28a0, v43
	s_add_u32 s4, s52, s4
	s_addc_u32 s5, s53, s5
	v_mov_b32_e32 v11, v9
	s_add_i32 s44, s44, s26
	s_waitcnt vmcnt(5)
	v_pk_mul_f32 v[0:1], v[30:31], v[4:5] op_sel_hi:[0,1]
	ds_write2_b32 v2, v0, v1 offset1:1
	v_pk_mul_f32 v[0:1], v[30:31], v[6:7] op_sel_hi:[0,1]
	v_add_u32_e32 v2, 0x28a8, v43
	ds_write2_b32 v2, v0, v1 offset1:1
	s_waitcnt vmcnt(4)
	v_pk_mul_f32 v[0:1], v[24:25], v[48:49] op_sel_hi:[0,1]
	v_add_u32_e32 v2, 0x2cb0, v43
	ds_write2_b32 v2, v0, v1 offset1:1
	v_pk_mul_f32 v[0:1], v[24:25], v[50:51] op_sel_hi:[0,1]
	v_add_u32_e32 v2, 0x2cb8, v43
	ds_write2_b32 v2, v0, v1 offset1:1
	s_waitcnt vmcnt(3)
	v_pk_mul_f32 v[0:1], v[36:37], v[52:53] op_sel_hi:[0,1]
	v_add_u32_e32 v2, 0x30c0, v43
	ds_write2_b32 v2, v0, v1 offset1:1
	v_pk_mul_f32 v[0:1], v[36:37], v[54:55] op_sel_hi:[0,1]
	v_add_u32_e32 v2, 0x30c8, v43
	ds_write2_b32 v2, v0, v1 offset1:1
	s_waitcnt vmcnt(2)
	v_pk_mul_f32 v[0:1], v[28:29], v[56:57] op_sel_hi:[0,1]
	v_add_u32_e32 v2, 0x34d0, v43
	ds_write2_b32 v2, v0, v1 offset1:1
	v_pk_mul_f32 v[0:1], v[28:29], v[58:59] op_sel_hi:[0,1]
	v_add_u32_e32 v2, 0x34d8, v43
	ds_write2_b32 v2, v0, v1 offset1:1
	s_waitcnt vmcnt(1)
	v_pk_mul_f32 v[0:1], v[40:41], v[76:77] op_sel_hi:[0,1]
	v_add_u32_e32 v2, 0x38e0, v43
	ds_write2_b32 v2, v0, v1 offset1:1
	v_pk_mul_f32 v[0:1], v[40:41], v[78:79] op_sel_hi:[0,1]
	v_add_u32_e32 v2, 0x38e8, v43
	ds_write2_b32 v2, v0, v1 offset1:1
	s_waitcnt vmcnt(0)
	v_pk_mul_f32 v[0:1], v[42:43], v[44:45] op_sel_hi:[0,1]
	v_add_u32_e32 v2, 0x3cf0, v43
	ds_write2_b32 v2, v0, v1 offset1:1
	v_pk_mul_f32 v[0:1], v[42:43], v[46:47] op_sel_hi:[0,1]
	v_add_u32_e32 v2, 0x3cf8, v43
	ds_write2_b32 v2, v0, v1 offset1:1
	s_waitcnt lgkmcnt(0)
	ds_read2_b32 v[0:1], v19 offset1:65
	s_waitcnt lgkmcnt(0)
	v_cvt_pk_bf16_f32 v0, v0, v1
	ds_read2_b32 v[2:3], v19 offset0:130 offset1:195
	s_waitcnt lgkmcnt(0)
	v_cvt_pk_bf16_f32 v1, v2, v3
	ds_read2_b32 v[2:3], v14 offset0:4 offset1:69
	s_waitcnt lgkmcnt(0)
	v_cvt_pk_bf16_f32 v2, v2, v3
	ds_read2_b32 v[4:5], v14 offset0:134 offset1:199
	v_lshl_add_u64 v[6:7], s[4:5], 0, v[10:11]
	v_add_u32_e32 v11, s45, v17
	s_waitcnt lgkmcnt(0)
	v_cvt_pk_bf16_f32 v3, v4, v5
	v_ashrrev_i32_e32 v4, 31, v11
	v_mul_lo_u32 v16, s48, v4
	v_mul_lo_u32 v18, s49, v11
	v_mad_u64_u32 v[12:13], s[4:5], s48, v11, 0
	v_add3_u32 v13, v13, v16, v18
	v_lshl_add_u64 v[12:13], v[12:13], 1, v[6:7]
	ds_read2_b32 v[4:5], v19 offset0:8 offset1:73
	global_store_dwordx4 v[12:13], v[0:3], off sc1
	v_add_u32_e32 v11, s45, v21
	v_mul_lo_u32 v18, s49, v11
	s_waitcnt lgkmcnt(0)
	v_cvt_pk_bf16_f32 v0, v4, v5
	ds_read2_b32 v[2:3], v19 offset0:138 offset1:203
	s_waitcnt lgkmcnt(0)
	v_cvt_pk_bf16_f32 v1, v2, v3
	ds_read2_b32 v[2:3], v14 offset0:12 offset1:77
	s_waitcnt lgkmcnt(0)
	v_cvt_pk_bf16_f32 v2, v2, v3
	ds_read2_b32 v[4:5], v14 offset0:142 offset1:207
	s_waitcnt lgkmcnt(0)
	v_cvt_pk_bf16_f32 v3, v4, v5
	v_ashrrev_i32_e32 v4, 31, v11
	v_mul_lo_u32 v16, s48, v4
	v_mad_u64_u32 v[12:13], s[4:5], s48, v11, 0
	v_add3_u32 v13, v13, v16, v18
	v_lshl_add_u64 v[12:13], v[12:13], 1, v[6:7]
	ds_read2_b32 v[4:5], v19 offset0:16 offset1:81
	global_store_dwordx4 v[12:13], v[0:3], off sc1
	v_add_u32_e32 v11, s45, v23
	v_mul_lo_u32 v18, s49, v11
	s_waitcnt lgkmcnt(0)
	v_cvt_pk_bf16_f32 v0, v4, v5
	ds_read2_b32 v[2:3], v19 offset0:146 offset1:211
	s_waitcnt lgkmcnt(0)
	v_cvt_pk_bf16_f32 v1, v2, v3
	ds_read2_b32 v[2:3], v14 offset0:20 offset1:85
	s_waitcnt lgkmcnt(0)
	v_cvt_pk_bf16_f32 v2, v2, v3
	ds_read2_b32 v[4:5], v14 offset0:150 offset1:215
	s_waitcnt lgkmcnt(0)
	v_cvt_pk_bf16_f32 v3, v4, v5
	v_ashrrev_i32_e32 v4, 31, v11
	v_mul_lo_u32 v16, s48, v4
	v_mad_u64_u32 v[12:13], s[4:5], s48, v11, 0
	v_add3_u32 v13, v13, v16, v18
	v_lshl_add_u64 v[12:13], v[12:13], 1, v[6:7]
	ds_read2_b32 v[4:5], v19 offset0:24 offset1:89
	global_store_dwordx4 v[12:13], v[0:3], off sc1
	v_add_u32_e32 v11, s45, v25
	v_mul_lo_u32 v18, s49, v11
	s_waitcnt lgkmcnt(0)
	v_cvt_pk_bf16_f32 v0, v4, v5
	ds_read2_b32 v[2:3], v19 offset0:154 offset1:219
	s_waitcnt lgkmcnt(0)
	v_cvt_pk_bf16_f32 v1, v2, v3
	ds_read2_b32 v[2:3], v14 offset0:28 offset1:93
	s_waitcnt lgkmcnt(0)
	v_cvt_pk_bf16_f32 v2, v2, v3
	ds_read2_b32 v[4:5], v14 offset0:158 offset1:223
	s_waitcnt lgkmcnt(0)
	v_cvt_pk_bf16_f32 v3, v4, v5
	v_ashrrev_i32_e32 v4, 31, v11
	v_mul_lo_u32 v16, s48, v4
	v_mad_u64_u32 v[12:13], s[4:5], s48, v11, 0
	v_add3_u32 v13, v13, v16, v18
	v_lshl_add_u64 v[12:13], v[12:13], 1, v[6:7]
	ds_read2_b32 v[4:5], v19 offset0:32 offset1:97
	global_store_dwordx4 v[12:13], v[0:3], off sc1
	v_add_u32_e32 v11, s45, v27
	v_mul_lo_u32 v18, s49, v11
	s_waitcnt lgkmcnt(0)
	v_cvt_pk_bf16_f32 v0, v4, v5
	ds_read2_b32 v[2:3], v19 offset0:162 offset1:227
	s_waitcnt lgkmcnt(0)
	v_cvt_pk_bf16_f32 v1, v2, v3
	ds_read2_b32 v[2:3], v14 offset0:36 offset1:101
	s_waitcnt lgkmcnt(0)
	v_cvt_pk_bf16_f32 v2, v2, v3
	ds_read2_b32 v[4:5], v14 offset0:166 offset1:231
	s_waitcnt lgkmcnt(0)
	v_cvt_pk_bf16_f32 v3, v4, v5
	v_ashrrev_i32_e32 v4, 31, v11
	v_mul_lo_u32 v16, s48, v4
	v_mad_u64_u32 v[12:13], s[4:5], s48, v11, 0
	v_add3_u32 v13, v13, v16, v18
	v_lshl_add_u64 v[12:13], v[12:13], 1, v[6:7]
	ds_read2_b32 v[4:5], v19 offset0:40 offset1:105
	global_store_dwordx4 v[12:13], v[0:3], off sc1
	v_add_u32_e32 v11, s45, v29
	v_mul_lo_u32 v18, s49, v11
	s_waitcnt lgkmcnt(0)
	v_cvt_pk_bf16_f32 v0, v4, v5
	ds_read2_b32 v[2:3], v19 offset0:170 offset1:235
	s_waitcnt lgkmcnt(0)
	v_cvt_pk_bf16_f32 v1, v2, v3
	ds_read2_b32 v[2:3], v14 offset0:44 offset1:109
	s_waitcnt lgkmcnt(0)
	v_cvt_pk_bf16_f32 v2, v2, v3
	ds_read2_b32 v[4:5], v14 offset0:174 offset1:239
	s_waitcnt lgkmcnt(0)
	v_cvt_pk_bf16_f32 v3, v4, v5
	v_ashrrev_i32_e32 v4, 31, v11
	v_mul_lo_u32 v16, s48, v4
	v_mad_u64_u32 v[12:13], s[4:5], s48, v11, 0
	v_add3_u32 v13, v13, v16, v18
	v_lshl_add_u64 v[12:13], v[12:13], 1, v[6:7]
	ds_read2_b32 v[4:5], v19 offset0:48 offset1:113
	global_store_dwordx4 v[12:13], v[0:3], off sc1
	v_add_u32_e32 v11, s45, v31
	v_mul_lo_u32 v18, s49, v11
	s_waitcnt lgkmcnt(0)
	v_cvt_pk_bf16_f32 v0, v4, v5
	ds_read2_b32 v[2:3], v19 offset0:178 offset1:243
	s_waitcnt lgkmcnt(0)
	v_cvt_pk_bf16_f32 v1, v2, v3
	ds_read2_b32 v[2:3], v14 offset0:52 offset1:117
	s_waitcnt lgkmcnt(0)
	v_cvt_pk_bf16_f32 v2, v2, v3
	ds_read2_b32 v[4:5], v14 offset0:182 offset1:247
	s_waitcnt lgkmcnt(0)
	v_cvt_pk_bf16_f32 v3, v4, v5
	v_ashrrev_i32_e32 v4, 31, v11
	v_mul_lo_u32 v16, s48, v4
	v_mad_u64_u32 v[12:13], s[4:5], s48, v11, 0
	v_add3_u32 v13, v13, v16, v18
	v_lshl_add_u64 v[12:13], v[12:13], 1, v[6:7]
	ds_read2_b32 v[4:5], v19 offset0:56 offset1:121
	global_store_dwordx4 v[12:13], v[0:3], off sc1
	s_cmp_ge_i32 s44, s23
	s_waitcnt lgkmcnt(0)
	v_cvt_pk_bf16_f32 v0, v4, v5
	ds_read2_b32 v[2:3], v19 offset0:186 offset1:251
	s_waitcnt lgkmcnt(0)
	v_cvt_pk_bf16_f32 v1, v2, v3
	ds_read2_b32 v[2:3], v14 offset0:60 offset1:125
	s_waitcnt lgkmcnt(0)
	v_cvt_pk_bf16_f32 v2, v2, v3
	ds_read2_b32 v[4:5], v14 offset0:190 offset1:255
	s_waitcnt lgkmcnt(0)
	v_cvt_pk_bf16_f32 v3, v4, v5
	v_add_u32_e32 v4, s45, v41
	v_ashrrev_i32_e32 v5, 31, v4
	v_mul_lo_u32 v11, s48, v5
	v_mul_lo_u32 v12, s49, v4
	v_mad_u64_u32 v[4:5], s[4:5], s48, v4, 0
	v_add3_u32 v5, v5, v11, v12
	v_lshl_add_u64 v[4:5], v[4:5], 1, v[6:7]
	global_store_dwordx4 v[4:5], v[0:3], off sc1
	s_waitcnt lgkmcnt(0)
	s_cbranch_scc1 .LBB0_61

.LBB0_67:
	s_or_b64 exec, exec, s[8:9]
	v_div_scale_f32 v62, s[8:9], v61, v61, 1.0
	v_rcp_f32_e32 v63, v62
	v_div_scale_f32 v64, vcc, 1.0, v61, 1.0
	s_lshl_b64 s[8:9], s[22:23], 11
	v_fma_f32 v65, -v62, v63, 1.0
	v_fmac_f32_e32 v63, v65, v63
	v_mul_f32_e32 v65, v64, v63
	v_fma_f32 v66, -v62, v65, v64
	v_fmac_f32_e32 v65, v66, v63
	v_fma_f32 v62, -v62, v65, v64
	v_div_fmas_f32 v62, v62, v63, v65
	v_div_fixup_f32 v61, v62, v61, 1.0
	v_mul_f32_e32 v12, v12, v61
	v_mul_f32_e32 v13, v13, v61
	v_cvt_pk_bf16_f32 v12, v12, v13
	v_mul_f32_e32 v13, v14, v61
	v_mul_f32_e32 v14, v15, v61
	v_cvt_pk_bf16_f32 v13, v13, v14
	v_mul_f32_e32 v14, v16, v61
	v_mul_f32_e32 v15, v17, v61
	v_cvt_pk_bf16_f32 v14, v14, v15
	v_mul_f32_e32 v15, v18, v61
	v_mul_f32_e32 v16, v19, v61
	v_cvt_pk_bf16_f32 v15, v15, v16
	v_cndmask_b32_e64 v16, v12, v14, s[6:7]
	v_cndmask_b32_e64 v17, v13, v15, s[6:7]
	ds_bpermute_b32 v16, v54, v16
	ds_bpermute_b32 v17, v54, v17
	v_mul_f32_e32 v4, v4, v61
	v_mul_f32_e32 v5, v5, v61
	s_sub_i32 s22, s10, s26
	s_waitcnt lgkmcnt(1)
	v_cndmask_b32_e64 v12, v16, v12, s[6:7]
	s_waitcnt lgkmcnt(0)
	v_cndmask_b32_e64 v13, v17, v13, s[6:7]
	v_cndmask_b32_e64 v14, v14, v16, s[6:7]
	v_cndmask_b32_e64 v15, v15, v17, s[6:7]
	v_lshl_add_u64 v[16:17], v[50:51], 0, s[8:9]
	global_store_dwordx4 v[16:17], v[12:15], off sc1
	v_cvt_pk_bf16_f32 v4, v4, v5
	v_mul_f32_e32 v5, v6, v61
	v_mul_f32_e32 v6, v7, v61
	v_cvt_pk_bf16_f32 v5, v5, v6
	v_mul_f32_e32 v6, v8, v61
	v_mul_f32_e32 v7, v9, v61
	v_cvt_pk_bf16_f32 v6, v6, v7
	v_mul_f32_e32 v7, v10, v61
	v_mul_f32_e32 v8, v11, v61
	v_cvt_pk_bf16_f32 v7, v7, v8
	v_cndmask_b32_e64 v8, v4, v6, s[6:7]
	v_cndmask_b32_e64 v9, v5, v7, s[6:7]
	ds_bpermute_b32 v8, v54, v8
	ds_bpermute_b32 v9, v54, v9
	s_cmpk_gt_i32 s22, 0x7fff
	v_mov_b32_e32 v12, v0
	v_mov_b32_e32 v13, v1
	s_waitcnt lgkmcnt(1)
	v_cndmask_b32_e64 v4, v8, v4, s[6:7]
	s_waitcnt lgkmcnt(0)
	v_cndmask_b32_e64 v5, v9, v5, s[6:7]
	v_cndmask_b32_e64 v6, v6, v8, s[6:7]
	v_cndmask_b32_e64 v7, v7, v9, s[6:7]
	global_store_dwordx4 v[16:17], v[4:7], off offset:1024 sc1
	v_mov_b32_e32 v14, v2
	v_mov_b32_e32 v15, v3
	v_mov_b32_e32 v16, v20
	v_mov_b32_e32 v17, v21
	v_mov_b32_e32 v18, v22
	v_mov_b32_e32 v19, v23
	v_mov_b32_e32 v4, v24
	v_mov_b32_e32 v5, v25
	v_mov_b32_e32 v6, v26
	v_mov_b32_e32 v7, v27
	v_mov_b32_e32 v8, v28
	v_mov_b32_e32 v9, v29
	v_mov_b32_e32 v10, v30
	v_mov_b32_e32 v11, v31
	v_mov_b32_e32 v0, v44
	v_mov_b32_e32 v1, v45
	v_mov_b32_e32 v2, v46
	v_mov_b32_e32 v3, v47
	v_mov_b32_e32 v20, v40
	v_mov_b32_e32 v21, v41
	v_mov_b32_e32 v22, v42
	v_mov_b32_e32 v23, v43
	v_mov_b32_e32 v24, v36
	v_mov_b32_e32 v25, v37
	v_mov_b32_e32 v26, v38
	v_mov_b32_e32 v27, v39
	v_mov_b32_e32 v28, v32
	v_mov_b32_e32 v29, v33
	v_mov_b32_e32 v30, v34
	v_mov_b32_e32 v31, v35
	s_cbranch_scc1 .LBB0_72

.LBB0_133:
	s_lshl_b32 s22, s28, 6
	s_mulk_i32 s27, 0x4200
	s_ashr_i32 s23, s22, 31
	s_add_i32 s11, s27, 0
	s_lshl_b64 s[22:23], s[22:23], 2
	s_waitcnt lgkmcnt(0)
	s_add_u32 s4, s4, s22
	v_lshlrev_b32_e32 v13, 4, v1
	s_addc_u32 s5, s5, s23
	v_and_b32_e32 v32, 0xf0, v13
	v_mov_b32_e32 v33, 0
	v_lshl_add_u64 v[84:85], s[4:5], 0, v[32:33]
	v_mul_lo_u32 v13, s21, v8
	v_mul_lo_u32 v9, s20, v9
	v_mad_u64_u32 v[36:37], s[4:5], s20, v8, 0
	v_add3_u32 v37, v37, v9, v13
	v_add_u32_e32 v9, 4, v8
	v_ashrrev_i32_e32 v13, 31, v9
	v_lshl_add_u64 v[44:45], v[36:37], 2, v[84:85]
	v_mul_lo_u32 v13, s20, v13
	v_mul_lo_u32 v15, s21, v9
	v_mad_u64_u32 v[36:37], s[4:5], s20, v9, 0
	v_add3_u32 v37, v37, v13, v15
	v_lshl_add_u64 v[46:47], v[36:37], 2, v[84:85]
	global_load_dwordx4 v[36:39], v[44:45], off nt
	global_load_dwordx4 v[40:43], v[46:47], off nt
	v_add_u32_e32 v9, 8, v8
	v_ashrrev_i32_e32 v13, 31, v9
	v_mul_lo_u32 v13, s20, v13
	v_mul_lo_u32 v15, s21, v9
	v_mad_u64_u32 v[44:45], s[4:5], s20, v9, 0
	v_add_u32_e32 v9, 12, v8
	v_add3_u32 v45, v45, v13, v15
	v_ashrrev_i32_e32 v13, 31, v9
	v_lshl_add_u64 v[52:53], v[44:45], 2, v[84:85]
	v_mul_lo_u32 v13, s20, v13
	v_mul_lo_u32 v15, s21, v9
	v_mad_u64_u32 v[44:45], s[4:5], s20, v9, 0
	v_add_u32_e32 v9, 16, v8
	v_add3_u32 v45, v45, v13, v15
	v_ashrrev_i32_e32 v13, 31, v9
	v_lshl_add_u64 v[54:55], v[44:45], 2, v[84:85]
	global_load_dwordx4 v[44:47], v[52:53], off nt
	global_load_dwordx4 v[48:51], v[54:55], off nt
	v_mul_lo_u32 v13, s20, v13
	v_mul_lo_u32 v15, s21, v9
	v_mad_u64_u32 v[52:53], s[4:5], s20, v9, 0
	v_add_u32_e32 v9, 20, v8
	v_add3_u32 v53, v53, v13, v15
	v_ashrrev_i32_e32 v13, 31, v9
	v_lshl_add_u64 v[60:61], v[52:53], 2, v[84:85]
	v_mul_lo_u32 v13, s20, v13
	v_mul_lo_u32 v15, s21, v9
	v_mad_u64_u32 v[52:53], s[4:5], s20, v9, 0
	v_add_u32_e32 v9, 24, v8
	v_add3_u32 v53, v53, v13, v15
	v_ashrrev_i32_e32 v13, 31, v9
	v_lshl_add_u64 v[62:63], v[52:53], 2, v[84:85]
	global_load_dwordx4 v[52:55], v[60:61], off nt
	global_load_dwordx4 v[56:59], v[62:63], off nt
	v_mul_lo_u32 v13, s20, v13
	v_mul_lo_u32 v15, s21, v9
	v_mad_u64_u32 v[60:61], s[4:5], s20, v9, 0
	v_add_u32_e32 v9, 28, v8
	v_add3_u32 v61, v61, v13, v15
	v_ashrrev_i32_e32 v13, 31, v9
	v_lshl_add_u64 v[68:69], v[60:61], 2, v[84:85]
	v_mul_lo_u32 v13, s20, v13
	v_mul_lo_u32 v15, s21, v9
	v_mad_u64_u32 v[60:61], s[4:5], s20, v9, 0
	v_add_u32_e32 v9, 32, v8
	v_add3_u32 v61, v61, v13, v15
	v_ashrrev_i32_e32 v13, 31, v9
	v_lshl_add_u64 v[70:71], v[60:61], 2, v[84:85]
	global_load_dwordx4 v[60:63], v[68:69], off nt
	global_load_dwordx4 v[64:67], v[70:71], off nt
	v_mul_lo_u32 v13, s20, v13
	v_mul_lo_u32 v15, s21, v9
	v_mad_u64_u32 v[68:69], s[4:5], s20, v9, 0
	v_add_u32_e32 v9, 36, v8
	v_add3_u32 v69, v69, v13, v15
	v_ashrrev_i32_e32 v13, 31, v9
	v_lshl_add_u64 v[76:77], v[68:69], 2, v[84:85]
	v_mul_lo_u32 v13, s20, v13
	v_mul_lo_u32 v15, s21, v9
	v_mad_u64_u32 v[68:69], s[4:5], s20, v9, 0
	v_add_u32_e32 v9, 40, v8
	v_add3_u32 v69, v69, v13, v15
	v_ashrrev_i32_e32 v13, 31, v9
	v_lshl_add_u64 v[78:79], v[68:69], 2, v[84:85]
	global_load_dwordx4 v[68:71], v[76:77], off nt
	global_load_dwordx4 v[72:75], v[78:79], off nt
	v_mul_lo_u32 v13, s20, v13
	v_mul_lo_u32 v15, s21, v9
	v_mad_u64_u32 v[76:77], s[4:5], s20, v9, 0
	v_add_u32_e32 v9, 44, v8
	v_add3_u32 v77, v77, v13, v15
	v_ashrrev_i32_e32 v13, 31, v9
	v_lshl_add_u64 v[86:87], v[76:77], 2, v[84:85]
	v_mul_lo_u32 v13, s20, v13
	v_mul_lo_u32 v15, s21, v9
	v_mad_u64_u32 v[76:77], s[4:5], s20, v9, 0
	v_add_u32_e32 v9, 48, v8
	v_add3_u32 v77, v77, v13, v15
	v_ashrrev_i32_e32 v13, 31, v9
	v_lshl_add_u64 v[88:89], v[76:77], 2, v[84:85]
	global_load_dwordx4 v[76:79], v[86:87], off nt
	global_load_dwordx4 v[80:83], v[88:89], off nt
	s_waitcnt vmcnt(11)
	v_pk_mul_f32 v[92:93], v[26:27], v[36:37] op_sel_hi:[0,1]
	v_mul_lo_u32 v13, s20, v13
	v_mul_lo_u32 v15, s21, v9
	v_mad_u64_u32 v[36:37], s[4:5], s20, v9, 0
	v_add3_u32 v37, v37, v13, v15
	v_add_u32_e32 v9, 52, v8
	v_add_u32_e32 v7, 60, v8
	v_lshl_add_u64 v[36:37], v[36:37], 2, v[84:85]
	v_ashrrev_i32_e32 v13, 31, v9
	v_add_u32_e32 v8, 56, v8
	v_pk_mul_f32 v[26:27], v[26:27], v[38:39] op_sel_hi:[0,1]
	s_waitcnt vmcnt(10)
	v_pk_mul_f32 v[94:95], v[16:17], v[40:41] op_sel_hi:[0,1]
	v_mul_lo_u32 v13, s20, v13
	v_mul_lo_u32 v15, s21, v9
	v_mad_u64_u32 v[40:41], s[4:5], s20, v9, 0
	v_ashrrev_i32_e32 v9, 31, v8
	global_load_dwordx4 v[36:39], v[36:37], off nt
	v_ashrrev_i32_e32 v11, 31, v7
	v_add3_u32 v41, v41, v13, v15
	v_mul_lo_u32 v13, s20, v9
	v_mul_lo_u32 v15, s21, v8
	v_mad_u64_u32 v[8:9], s[4:5], s20, v8, 0
	v_pk_mul_f32 v[16:17], v[16:17], v[42:43] op_sel_hi:[0,1]
	v_add3_u32 v9, v9, v13, v15
	v_mul_lo_u32 v11, s20, v11
	v_mul_lo_u32 v13, s21, v7
	v_mad_u64_u32 v[42:43], s[4:5], s20, v7, 0
	v_add3_u32 v43, v43, v11, v13
	v_lshl_add_u64 v[96:97], v[40:41], 2, v[84:85]
	v_lshl_add_u64 v[8:9], v[8:9], 2, v[84:85]
	v_lshl_add_u64 v[98:99], v[42:43], 2, v[84:85]
	global_load_dwordx4 v[40:43], v[96:97], off nt
	global_load_dwordx4 v[84:87], v[8:9], off nt
	global_load_dwordx4 v[88:91], v[98:99], off nt
	s_movk_i32 s4, 0x104
	v_mul_lo_u32 v5, v5, s4
	v_add3_u32 v7, s11, v32, v5
	v_add_u32_e32 v5, 0x410, v7
	ds_write2_b32 v5, v94, v95 offset1:1
	ds_write2_b32 v7, v92, v93 offset1:1
	ds_write2_b32 v7, v26, v27 offset0:2 offset1:3
	v_add_u32_e32 v5, 0x418, v7
	ds_write2_b32 v5, v16, v17 offset1:1
	v_add_u32_e32 v5, 0x820, v7
	s_waitcnt vmcnt(13)
	v_pk_mul_f32 v[8:9], v[4:5], v[44:45] op_sel_hi:[0,1]
	ds_write2_b32 v5, v8, v9 offset1:1
	v_add_u32_e32 v8, 0x828, v7
	v_pk_mul_f32 v[4:5], v[4:5], v[46:47] op_sel_hi:[0,1]
	ds_write2_b32 v8, v4, v5 offset1:1
	v_add_u32_e32 v8, 0xc30, v7
	s_waitcnt vmcnt(12)
	v_pk_mul_f32 v[4:5], v[0:1], v[48:49] op_sel_hi:[0,1]
	ds_write2_b32 v8, v4, v5 offset1:1
	v_add_u32_e32 v8, 0xc38, v7
	v_pk_mul_f32 v[4:5], v[0:1], v[50:51] op_sel_hi:[0,1]
	ds_write2_b32 v8, v4, v5 offset1:1
	v_add_u32_e32 v0, 0x1040, v7
	s_waitcnt vmcnt(11)
	v_pk_mul_f32 v[4:5], v[10:11], v[52:53] op_sel_hi:[0,1]
	ds_write2_b32 v0, v4, v5 offset1:1
	v_add_u32_e32 v0, 0x1048, v7
	v_pk_mul_f32 v[4:5], v[10:11], v[54:55] op_sel_hi:[0,1]
	ds_write2_b32 v0, v4, v5 offset1:1
	v_add_u32_e32 v0, 0x1450, v7
	s_waitcnt vmcnt(10)
	v_pk_mul_f32 v[4:5], v[2:3], v[56:57] op_sel_hi:[0,1]
	ds_write2_b32 v0, v4, v5 offset1:1
	v_add_u32_e32 v0, 0x1458, v7
	v_pk_mul_f32 v[4:5], v[2:3], v[58:59] op_sel_hi:[0,1]
	ds_write2_b32 v0, v4, v5 offset1:1
	v_add_u32_e32 v0, 0x1860, v7
	s_waitcnt vmcnt(9)
	v_pk_mul_f32 v[4:5], v[14:15], v[60:61] op_sel_hi:[0,1]
	ds_write2_b32 v0, v4, v5 offset1:1
	v_add_u32_e32 v0, 0x1868, v7
	v_pk_mul_f32 v[4:5], v[14:15], v[62:63] op_sel_hi:[0,1]
	ds_write2_b32 v0, v4, v5 offset1:1
	v_add_u32_e32 v0, 0x1c70, v7
	s_waitcnt vmcnt(8)
	v_pk_mul_f32 v[4:5], v[6:7], v[64:65] op_sel_hi:[0,1]
	ds_write2_b32 v0, v4, v5 offset1:1
	v_add_u32_e32 v0, 0x1c78, v7
	v_pk_mul_f32 v[4:5], v[6:7], v[66:67] op_sel_hi:[0,1]
	ds_write2_b32 v0, v4, v5 offset1:1
	v_add_u32_e32 v0, 0x2080, v7
	s_waitcnt vmcnt(7)
	v_pk_mul_f32 v[4:5], v[20:21], v[68:69] op_sel_hi:[0,1]
	ds_write2_b32 v0, v4, v5 offset1:1
	v_add_u32_e32 v0, 0x2088, v7
	v_pk_mul_f32 v[4:5], v[20:21], v[70:71] op_sel_hi:[0,1]
	ds_write2_b32 v0, v4, v5 offset1:1
	v_add_u32_e32 v0, 0x2490, v7
	s_waitcnt vmcnt(6)
	v_pk_mul_f32 v[4:5], v[12:13], v[72:73] op_sel_hi:[0,1]
	ds_write2_b32 v0, v4, v5 offset1:1
	v_add_u32_e32 v0, 0x2498, v7
	v_pk_mul_f32 v[4:5], v[12:13], v[74:75] op_sel_hi:[0,1]
	ds_write2_b32 v0, v4, v5 offset1:1
	v_add_u32_e32 v0, 0x28a0, v7
	s_waitcnt vmcnt(5)
	v_pk_mul_f32 v[4:5], v[24:25], v[76:77] op_sel_hi:[0,1]
	ds_write2_b32 v0, v4, v5 offset1:1
	v_add_u32_e32 v0, 0x28a8, v7
	v_pk_mul_f32 v[4:5], v[24:25], v[78:79] op_sel_hi:[0,1]
	ds_write2_b32 v0, v4, v5 offset1:1
	v_add_u32_e32 v0, 0x2cb0, v7
	s_waitcnt vmcnt(4)
	v_pk_mul_f32 v[4:5], v[18:19], v[80:81] op_sel_hi:[0,1]
	ds_write2_b32 v0, v4, v5 offset1:1
	v_add_u32_e32 v0, 0x2cb8, v7
	v_pk_mul_f32 v[4:5], v[18:19], v[82:83] op_sel_hi:[0,1]
	ds_write2_b32 v0, v4, v5 offset1:1
	v_add_u32_e32 v0, 0x30c0, v7
	s_waitcnt vmcnt(3)
	v_pk_mul_f32 v[4:5], v[28:29], v[36:37] op_sel_hi:[0,1]
	ds_write2_b32 v0, v4, v5 offset1:1
	v_add_u32_e32 v0, 0x30c8, v7
	v_pk_mul_f32 v[4:5], v[28:29], v[38:39] op_sel_hi:[0,1]
	ds_write2_b32 v0, v4, v5 offset1:1
	v_add_u32_e32 v0, 0x34d0, v7
	v_ashrrev_i32_e32 v2, 3, v1
	s_waitcnt vmcnt(2)
	v_pk_mul_f32 v[4:5], v[22:23], v[40:41] op_sel_hi:[0,1]
	ds_write2_b32 v0, v4, v5 offset1:1
	v_add_u32_e32 v0, 0x34d8, v7
	v_pk_mul_f32 v[4:5], v[22:23], v[42:43] op_sel_hi:[0,1]
	ds_write2_b32 v0, v4, v5 offset1:1
	v_add_u32_e32 v0, 0x38e0, v7
	s_waitcnt vmcnt(1)
	v_pk_mul_f32 v[4:5], v[30:31], v[84:85] op_sel_hi:[0,1]
	ds_write2_b32 v0, v4, v5 offset1:1
	v_add_u32_e32 v0, 0x38e8, v7
	v_pk_mul_f32 v[4:5], v[30:31], v[86:87] op_sel_hi:[0,1]
	ds_write2_b32 v0, v4, v5 offset1:1
	v_add_u32_e32 v0, 0x3cf0, v7
	s_waitcnt vmcnt(0)
	v_pk_mul_f32 v[4:5], v[34:35], v[88:89] op_sel_hi:[0,1]
	ds_write2_b32 v0, v4, v5 offset1:1
	v_add_u32_e32 v0, 0x3cf8, v7
	v_pk_mul_f32 v[4:5], v[34:35], v[90:91] op_sel_hi:[0,1]
	ds_write2_b32 v0, v4, v5 offset1:1
	v_lshlrev_b32_e32 v0, 3, v1
	v_and_b32_e32 v7, 56, v0
	s_waitcnt lgkmcnt(0)
	v_mul_u32_u24_e32 v0, 0x104, v7
	v_lshlrev_b32_e32 v1, 2, v2
	v_add3_u32 v12, s11, v0, v1
	ds_read2_b32 v[0:1], v12 offset1:65
	s_waitcnt lgkmcnt(0)
	v_cvt_pk_bf16_f32 v4, v0, v1
	ds_read2_b32 v[0:1], v12 offset0:130 offset1:195
	v_add_u32_e32 v13, 0x400, v12
	s_ashr_i32 s11, s10, 31
	s_waitcnt lgkmcnt(0)
	v_cvt_pk_bf16_f32 v5, v0, v1
	ds_read2_b32 v[0:1], v13 offset0:4 offset1:69
	s_lshl_b64 s[4:5], s[10:11], 1
	s_waitcnt lgkmcnt(0)
	v_cvt_pk_bf16_f32 v6, v0, v1
	ds_read2_b32 v[0:1], v13 offset0:134 offset1:199
	s_add_u32 s4, s8, s4
	v_add_u32_e32 v2, s26, v2
	s_addc_u32 s5, s9, s5
	v_lshlrev_b32_e32 v32, 1, v7
	s_waitcnt lgkmcnt(0)
	v_cvt_pk_bf16_f32 v7, v0, v1
	v_ashrrev_i32_e32 v0, 31, v2
	v_lshl_add_u64 v[8:9], s[4:5], 0, v[32:33]
	v_mul_lo_u32 v14, s6, v0
	v_mul_lo_u32 v15, s7, v2
	v_mad_u64_u32 v[10:11], s[4:5], s6, v2, 0
	v_add3_u32 v11, v11, v14, v15
	ds_read2_b32 v[0:1], v12 offset0:8 offset1:73
	v_lshl_add_u64 v[10:11], v[10:11], 1, v[8:9]
	global_store_dwordx4 v[10:11], v[4:7], off sc1
	v_add_u32_e32 v10, 8, v2
	v_mul_lo_u32 v15, s7, v10
	s_waitcnt lgkmcnt(0)
	v_cvt_pk_bf16_f32 v4, v0, v1
	ds_read2_b32 v[0:1], v12 offset0:138 offset1:203
	s_waitcnt lgkmcnt(0)
	v_cvt_pk_bf16_f32 v5, v0, v1
	ds_read2_b32 v[0:1], v13 offset0:12 offset1:77
	s_waitcnt lgkmcnt(0)
	v_cvt_pk_bf16_f32 v6, v0, v1
	ds_read2_b32 v[0:1], v13 offset0:142 offset1:207
	s_waitcnt lgkmcnt(0)
	v_cvt_pk_bf16_f32 v7, v0, v1
	v_ashrrev_i32_e32 v0, 31, v10
	v_mul_lo_u32 v14, s6, v0
	v_mad_u64_u32 v[10:11], s[4:5], s6, v10, 0
	v_add3_u32 v11, v11, v14, v15
	ds_read2_b32 v[0:1], v12 offset0:16 offset1:81
	v_lshl_add_u64 v[10:11], v[10:11], 1, v[8:9]
	global_store_dwordx4 v[10:11], v[4:7], off sc1
	v_add_u32_e32 v10, 16, v2
	v_mul_lo_u32 v15, s7, v10
	s_waitcnt lgkmcnt(0)
	v_cvt_pk_bf16_f32 v4, v0, v1
	ds_read2_b32 v[0:1], v12 offset0:146 offset1:211
	s_waitcnt lgkmcnt(0)
	v_cvt_pk_bf16_f32 v5, v0, v1
	ds_read2_b32 v[0:1], v13 offset0:20 offset1:85
	s_waitcnt lgkmcnt(0)
	v_cvt_pk_bf16_f32 v6, v0, v1
	ds_read2_b32 v[0:1], v13 offset0:150 offset1:215
	s_waitcnt lgkmcnt(0)
	v_cvt_pk_bf16_f32 v7, v0, v1
	v_ashrrev_i32_e32 v0, 31, v10
	v_mul_lo_u32 v14, s6, v0
	v_mad_u64_u32 v[10:11], s[4:5], s6, v10, 0
	v_add3_u32 v11, v11, v14, v15
	ds_read2_b32 v[0:1], v12 offset0:24 offset1:89
	v_lshl_add_u64 v[10:11], v[10:11], 1, v[8:9]
	global_store_dwordx4 v[10:11], v[4:7], off sc1
	v_add_u32_e32 v10, 24, v2
	v_mul_lo_u32 v15, s7, v10
	s_waitcnt lgkmcnt(0)
	v_cvt_pk_bf16_f32 v4, v0, v1
	ds_read2_b32 v[0:1], v12 offset0:154 offset1:219
	s_waitcnt lgkmcnt(0)
	v_cvt_pk_bf16_f32 v5, v0, v1
	ds_read2_b32 v[0:1], v13 offset0:28 offset1:93
	s_waitcnt lgkmcnt(0)
	v_cvt_pk_bf16_f32 v6, v0, v1
	ds_read2_b32 v[0:1], v13 offset0:158 offset1:223
	s_waitcnt lgkmcnt(0)
	v_cvt_pk_bf16_f32 v7, v0, v1
	v_ashrrev_i32_e32 v0, 31, v10
	v_mul_lo_u32 v14, s6, v0
	v_mad_u64_u32 v[10:11], s[4:5], s6, v10, 0
	v_add3_u32 v11, v11, v14, v15
	ds_read2_b32 v[0:1], v12 offset0:32 offset1:97
	v_lshl_add_u64 v[10:11], v[10:11], 1, v[8:9]
	global_store_dwordx4 v[10:11], v[4:7], off sc1
	v_add_u32_e32 v10, 32, v2
	v_mul_lo_u32 v15, s7, v10
	s_waitcnt lgkmcnt(0)
	v_cvt_pk_bf16_f32 v4, v0, v1
	ds_read2_b32 v[0:1], v12 offset0:162 offset1:227
	s_waitcnt lgkmcnt(0)
	v_cvt_pk_bf16_f32 v5, v0, v1
	ds_read2_b32 v[0:1], v13 offset0:36 offset1:101
	s_waitcnt lgkmcnt(0)
	v_cvt_pk_bf16_f32 v6, v0, v1
	ds_read2_b32 v[0:1], v13 offset0:166 offset1:231
	s_waitcnt lgkmcnt(0)
	v_cvt_pk_bf16_f32 v7, v0, v1
	v_ashrrev_i32_e32 v0, 31, v10
	v_mul_lo_u32 v14, s6, v0
	v_mad_u64_u32 v[10:11], s[4:5], s6, v10, 0
	v_add3_u32 v11, v11, v14, v15
	ds_read2_b32 v[0:1], v12 offset0:40 offset1:105
	v_lshl_add_u64 v[10:11], v[10:11], 1, v[8:9]
	global_store_dwordx4 v[10:11], v[4:7], off sc1
	v_add_u32_e32 v10, 40, v2
	v_mul_lo_u32 v15, s7, v10
	s_waitcnt lgkmcnt(0)
	v_cvt_pk_bf16_f32 v4, v0, v1
	ds_read2_b32 v[0:1], v12 offset0:170 offset1:235
	s_waitcnt lgkmcnt(0)
	v_cvt_pk_bf16_f32 v5, v0, v1
	ds_read2_b32 v[0:1], v13 offset0:44 offset1:109
	s_waitcnt lgkmcnt(0)
	v_cvt_pk_bf16_f32 v6, v0, v1
	ds_read2_b32 v[0:1], v13 offset0:174 offset1:239
	s_waitcnt lgkmcnt(0)
	v_cvt_pk_bf16_f32 v7, v0, v1
	v_ashrrev_i32_e32 v0, 31, v10
	v_mul_lo_u32 v14, s6, v0
	v_mad_u64_u32 v[10:11], s[4:5], s6, v10, 0
	v_add3_u32 v11, v11, v14, v15
	ds_read2_b32 v[0:1], v12 offset0:48 offset1:113
	v_lshl_add_u64 v[10:11], v[10:11], 1, v[8:9]
	global_store_dwordx4 v[10:11], v[4:7], off sc1
	v_add_u32_e32 v10, 48, v2
	v_mul_lo_u32 v15, s7, v10
	s_waitcnt lgkmcnt(0)
	v_cvt_pk_bf16_f32 v4, v0, v1
	ds_read2_b32 v[0:1], v12 offset0:178 offset1:243
	s_waitcnt lgkmcnt(0)
	v_cvt_pk_bf16_f32 v5, v0, v1
	ds_read2_b32 v[0:1], v13 offset0:52 offset1:117
	s_waitcnt lgkmcnt(0)
	v_cvt_pk_bf16_f32 v6, v0, v1
	ds_read2_b32 v[0:1], v13 offset0:182 offset1:247
	s_waitcnt lgkmcnt(0)
	v_cvt_pk_bf16_f32 v7, v0, v1
	v_ashrrev_i32_e32 v0, 31, v10
	v_mul_lo_u32 v14, s6, v0
	v_mad_u64_u32 v[10:11], s[4:5], s6, v10, 0
	v_add3_u32 v11, v11, v14, v15
	ds_read2_b32 v[0:1], v12 offset0:56 offset1:121
	v_lshl_add_u64 v[10:11], v[10:11], 1, v[8:9]
	global_store_dwordx4 v[10:11], v[4:7], off sc1
	s_waitcnt lgkmcnt(0)
	s_nop 0
	v_cvt_pk_bf16_f32 v4, v0, v1
	ds_read2_b32 v[0:1], v12 offset0:186 offset1:251
	s_waitcnt lgkmcnt(0)
	v_cvt_pk_bf16_f32 v5, v0, v1
	ds_read2_b32 v[0:1], v13 offset0:60 offset1:125
	s_waitcnt lgkmcnt(0)
	v_cvt_pk_bf16_f32 v6, v0, v1
	ds_read2_b32 v[0:1], v13 offset0:190 offset1:255
	s_waitcnt lgkmcnt(0)
	v_cvt_pk_bf16_f32 v7, v0, v1
	v_add_u32_e32 v0, 56, v2
	v_ashrrev_i32_e32 v1, 31, v0
	v_mul_lo_u32 v2, s6, v1
	v_mul_lo_u32 v10, s7, v0
	v_mad_u64_u32 v[0:1], s[4:5], s6, v0, 0
	v_add3_u32 v1, v1, v2, v10
	v_lshl_add_u64 v[0:1], v[0:1], 1, v[8:9]
	global_store_dwordx4 v[0:1], v[4:7], off sc1
	s_waitcnt lgkmcnt(0)
